# od / mlp row-norm passes: wait for the next row's prefetched data moved from the middle of the row's output part to its end (vmcnt(4)), gain loads waited once where they are issued
# speedup vs baseline: 1.0040x; 1.0040x over previous
; DEVI unsigned pk_bf16(float lo, float hi) { unsigned r; asm("v_cvt_pk_bf16_f32 %0, %1, %2" : "=v"(r) : "v"(lo), "v"(hi)); return r; }
; DEVI float wave_sum(float v) { for (int o = 32; o; o >>= 1) v += __shfl_xor(v, o); return v; }
; __device__ __forceinline__ void norm_phase(const Params& p, const float* __restrict__ gain, int mode, int nslab) {
;     ...
;   if (wave < M) { const float* src = srcrow(wave);
; #pragma unroll
;     for (int i = 0; i < 4; ++i) vn[i] = *(const float4*)(src + i * 256 + lane * 4); }
;   for (int r = wave; r < M; r += nw) {
;     float* hp = hrow(p, r);
; #pragma unroll
;     for (int i = 0; i < 4; ++i) v[i] = vn[i];
;     if (r + nw < M) { const float* src = srcrow(r + nw);
; #pragma unroll
;       for (int i = 0; i < 4; ++i) vn[i] = *(const float4*)(src + i * 256 + lane * 4); }
;     if (nslab > 0 && r >= 32768) {
;       const float* sl = (const float*)(p.ws + OFF_SLAB) + (size_t)(r - 32768) * 1024 + lane * 4;
;       for (int sI = 0; sI < nslab; ++sI)
; #pragma unroll
;         for (int i = 0; i < 4; ++i) { const float4 a = *(const float4*)(sl + (size_t)sI * 131072 + i * 256); v[i].x += a.x; v[i].y += a.y; v[i].z += a.z; v[i].w += a.w; }
; #pragma unroll
;       for (int i = 0; i < 4; ++i) *(float4*)(hp + i * 256 + lane * 4) = v[i];
;     }
;     float ss = 0.f;
; #pragma unroll
;     for (int i = 0; i < 4; ++i) ss += v[i].x * v[i].x + v[i].y * v[i].y + v[i].z * v[i].z + v[i].w * v[i].w;
;     ss = wave_sum(ss);
;     const float rs = rsqrtf(ss * (1.0f / 1024.0f) + EPS);
; #pragma unroll
;     for (int i = 0; i < 4; ++i) {
;       const float4 g = *(const float4*)(gain + i * 256 + lane * 4);
;       uint2 w; w.x = pk_bf16(v[i].x * rs * g.x, v[i].y * rs * g.y); w.y = pk_bf16(v[i].z * rs * g.z, v[i].w * rs * g.w);
;       *(uint2*)(xn + (size_t)r * 1024 + i * 256 + lane * 4) = w;
;     }
;   }
.LBB0_1016:
	s_andn2_saveexec_b64 s[0:1], s[0:1]
	v_lshl_add_u32 v0, v2, 4, v7
	v_ashrrev_i32_e32 v1, 31, v0
	v_mov_b64_e32 v[4:5], s[14:15]
	s_or_b64 exec, exec, s[0:1]
	v_lshlrev_b64 v[0:1], 12, v[0:1]
	v_lshlrev_b32_e32 v2, 2, v6
	v_lshl_add_u64 v[0:1], v[4:5], 0, v[0:1]
	v_and_b32_e32 v4, 0xfc, v2
	v_lshlrev_b32_e32 v8, 2, v4
	v_mov_b32_e32 v9, v130
	v_lshl_add_u64 v[0:1], v[0:1], 0, v[8:9]
	global_load_dwordx4 v[20:23], v[0:1], off offset:3072
	global_load_dwordx4 v[24:27], v[0:1], off offset:2048
	global_load_dwordx4 v[28:31], v[0:1], off offset:1024
	global_load_dwordx4 v[32:35], v[0:1], off
	v_readlane_b32 s36, v253, 8
	v_readlane_b32 s50, v253, 22
	v_readlane_b32 s51, v253, 23
	v_cmp_lt_i32_e32 vcc, v185, v184
	s_mov_b64 s[18:19], s[50:51]
	v_readlane_b32 s0, v254, 18
	v_cndmask_b32_e32 v5, v183, v185, vcc
	v_cmp_lt_i32_e32 vcc, v186, v184
	global_load_dwordx4 v[0:3], v8, s[50:51]
	v_lshlrev_b32_e32 v56, 2, v5
	v_cndmask_b32_e32 v5, v183, v186, vcc
	v_cmp_lt_i32_e32 vcc, v187, v184
	v_lshlrev_b32_e32 v57, 2, v5
	v_readlane_b32 s4, v253, 2
	v_cndmask_b32_e32 v5, v183, v187, vcc
	v_cmp_lt_i32_e32 vcc, v191, v184
	v_lshlrev_b32_e32 v58, 2, v5
	v_lshl_add_u64 v[36:37], s[18:19], 0, v[8:9]
	global_load_dwordx4 v[112:115], v[36:37], off offset:1024
	global_load_dwordx4 v[116:119], v[36:37], off offset:2048
	global_load_dwordx4 v[120:123], v[36:37], off offset:3072
	s_waitcnt vmcnt(0)
	v_cndmask_b32_e32 v5, v183, v191, vcc
	v_cmp_lt_i32_e32 vcc, v192, v184
	v_lshlrev_b32_e32 v59, 2, v5
	v_lshlrev_b32_e32 v8, 1, v4
	v_cndmask_b32_e32 v5, v183, v192, vcc
	v_cmp_lt_i32_e32 vcc, v190, v184
	v_lshlrev_b32_e32 v60, 2, v5
	v_readlane_b32 s1, v254, 19
	v_cndmask_b32_e32 v5, v183, v190, vcc
	v_lshlrev_b32_e32 v61, 2, v5
	v_and_b32_e32 v5, 63, v6
	v_lshlrev_b32_e32 v6, 4, v5
	v_mov_b32_e32 v7, v130
	v_readlane_b32 s5, v253, 3
	v_readlane_b32 s6, v253, 4
	v_readlane_b32 s7, v253, 5
	v_lshl_add_u64 v[38:39], s[0:1], 0, v[8:9]
	v_add_u32_e32 v42, 0xffff8000, v46
	v_lshl_add_u64 v[40:41], s[6:7], 0, v[6:7]
	s_mov_b64 s[4:5], 0
	v_lshlrev_b32_e32 v44, 2, v4
	v_readlane_b32 s37, v253, 9
	v_readlane_b32 s38, v253, 10
	v_readlane_b32 s39, v253, 11
	v_readlane_b32 s40, v253, 12
	v_readlane_b32 s41, v253, 13
	v_readlane_b32 s42, v253, 14
	v_readlane_b32 s43, v253, 15
	v_readlane_b32 s44, v253, 16
	v_readlane_b32 s45, v253, 17
	v_readlane_b32 s46, v253, 18
	v_readlane_b32 s47, v253, 19
	v_readlane_b32 s48, v253, 20
	v_readlane_b32 s49, v253, 21
	s_branch .LBB0_1020
.LBB0_1019:
	s_or_b64 exec, exec, s[0:1]
	v_mov_b32_e32 v48, v28
	v_mov_b32_e32 v49, v32
	v_pk_mul_f32 v[48:49], v[48:49], v[48:49]
	v_mov_b32_e32 v50, v29
	v_mov_b32_e32 v51, v33
	v_pk_fma_f32 v[48:49], v[50:51], v[50:51], v[48:49]
	v_mov_b32_e32 v50, v30
	v_mov_b32_e32 v51, v34
	v_pk_fma_f32 v[48:49], v[50:51], v[50:51], v[48:49]
	v_mov_b32_e32 v50, v31
	v_mov_b32_e32 v51, v35
	v_pk_fma_f32 v[48:49], v[50:51], v[50:51], v[48:49]
	v_mov_b32_e32 v50, v20
	v_mov_b32_e32 v51, v24
	v_pk_mul_f32 v[50:51], v[50:51], v[50:51]
	v_mov_b32_e32 v52, v21
	v_mov_b32_e32 v53, v25
	v_pk_fma_f32 v[50:51], v[52:53], v[52:53], v[50:51]
	v_mov_b32_e32 v52, v22
	v_mov_b32_e32 v53, v26
	v_pk_fma_f32 v[50:51], v[52:53], v[52:53], v[50:51]
	v_mov_b32_e32 v52, v23
	v_mov_b32_e32 v53, v27
	v_pk_fma_f32 v[50:51], v[52:53], v[52:53], v[50:51]
	v_add_f32_e32 v43, v48, v49
	v_add_f32_e32 v43, v51, v43
	v_add_f32_e32 v43, v50, v43
	v_ashrrev_i32_e32 v47, 31, v46
	v_lshlrev_b64 v[46:47], 11, v[46:47]
	v_lshl_add_u64 v[46:47], v[38:39], 0, v[46:47]
	v_add_u32_e32 v42, s80, v42
	s_nop 1
	v_add_f32_dpp v43, v43, v43 row_shr:1 row_mask:0xf bank_mask:0xf
	s_nop 1
	v_add_f32_dpp v43, v43, v43 row_shr:2 row_mask:0xf bank_mask:0xf
	s_nop 1
	v_add_f32_dpp v43, v43, v43 row_shr:4 row_mask:0xf bank_mask:0xf
	s_nop 1
	v_add_f32_dpp v43, v43, v43 row_shr:8 row_mask:0xf bank_mask:0xf
	s_nop 1
	v_add_f32_dpp v43, v43, v43 row_bcast:15 row_mask:0xa bank_mask:0xf
	s_nop 1
	v_add_f32_dpp v43, v43, v43 row_bcast:31 row_mask:0xc bank_mask:0xf
	s_nop 0
	v_readlane_b32 s98, v43, 63
	s_nop 1
	v_mov_b32_e32 v43, s98
	v_fmamk_f32 v43, v43, 0x3a800000, v132
	v_cmp_gt_f32_e32 vcc, s82, v43
	v_mul_f32_e32 v45, 0x4b800000, v43
	s_nop 0
	v_cndmask_b32_e32 v43, v43, v45, vcc
	v_rsq_f32_e32 v43, v43
	s_nop 0
	v_mul_f32_e32 v45, 0x45800000, v43
	v_cndmask_b32_e32 v43, v43, v45, vcc
	v_mul_f32_e32 v32, v32, v43
	v_mul_f32_e32 v33, v33, v43
	v_mul_f32_e32 v32, v0, v32
	v_mul_f32_e32 v33, v1, v33
	v_cvt_pk_bf16_f32 v32, v32, v33
	v_mul_f32_e32 v33, v34, v43
	v_mul_f32_e32 v33, v2, v33
	v_mul_f32_e32 v34, v35, v43
	v_mul_f32_e32 v34, v3, v34
	v_cvt_pk_bf16_f32 v33, v33, v34
	global_store_dwordx2 v[46:47], v[32:33], off
	v_mul_f32_e32 v28, v28, v43
	v_mul_f32_e32 v29, v29, v43
	v_mul_f32_e32 v24, v24, v43
	v_mul_f32_e32 v25, v25, v43
	v_mul_f32_e32 v20, v20, v43
	v_mul_f32_e32 v21, v21, v43
	v_mov_b64_e32 v[32:33], v[112:113]
	v_mov_b64_e32 v[34:35], v[114:115]
	v_mul_f32_e32 v28, v32, v28
	v_mul_f32_e32 v29, v33, v29
	v_cvt_pk_bf16_f32 v28, v28, v29
	v_mul_f32_e32 v29, v30, v43
	v_mul_f32_e32 v29, v34, v29
	v_mul_f32_e32 v30, v31, v43
	v_mul_f32_e32 v30, v35, v30
	v_cvt_pk_bf16_f32 v29, v29, v30
	global_store_dwordx2 v[46:47], v[28:29], off offset:512
	v_mov_b64_e32 v[28:29], v[116:117]
	v_mov_b64_e32 v[30:31], v[118:119]
	v_mul_f32_e32 v24, v28, v24
	v_mul_f32_e32 v25, v29, v25
	v_cvt_pk_bf16_f32 v24, v24, v25
	v_mul_f32_e32 v25, v26, v43
	v_mul_f32_e32 v25, v30, v25
	v_mul_f32_e32 v26, v27, v43
	v_mul_f32_e32 v26, v26, v31
	v_cvt_pk_bf16_f32 v25, v25, v26
	global_store_dwordx2 v[46:47], v[24:25], off offset:1024
	v_mov_b64_e32 v[24:25], v[120:121]
	v_mov_b64_e32 v[26:27], v[122:123]
	v_mul_f32_e32 v20, v20, v24
	v_mul_f32_e32 v21, v21, v25
	v_cvt_pk_bf16_f32 v20, v20, v21
	v_mul_f32_e32 v21, v22, v43
	v_mul_f32_e32 v21, v21, v26
	v_mul_f32_e32 v22, v23, v43
	v_mul_f32_e32 v22, v22, v27
	v_cvt_pk_bf16_f32 v21, v21, v22
	global_store_dwordx2 v[46:47], v[20:21], off offset:1536
	s_waitcnt vmcnt(4)
	v_mov_b64_e32 v[34:35], v[6:7]
	v_mov_b64_e32 v[32:33], v[4:5]
	v_mov_b64_e32 v[30:31], v[10:11]
	v_mov_b64_e32 v[28:29], v[8:9]
	v_mov_b32_e32 v46, v62
	v_mov_b64_e32 v[22:23], v[18:19]
	v_mov_b64_e32 v[20:21], v[16:17]
	v_mov_b64_e32 v[26:27], v[14:15]
	v_mov_b64_e32 v[24:25], v[12:13]
	s_andn2_b64 exec, exec, s[4:5]
	s_cbranch_execz .LBB0_1034

; DEVI unsigned pk_bf16(float lo, float hi) { unsigned r; asm("v_cvt_pk_bf16_f32 %0, %1, %2" : "=v"(r) : "v"(lo), "v"(hi)); return r; }
; DEVI float wave_sum(float v) { for (int o = 32; o; o >>= 1) v += __shfl_xor(v, o); return v; }
; __device__ __forceinline__ void norm_phase(const Params& p, const float* __restrict__ gain, int mode, int nslab) {
;     ...
;   if (wave < M) { const float* src = srcrow(wave);
; #pragma unroll
;     for (int i = 0; i < 4; ++i) vn[i] = *(const float4*)(src + i * 256 + lane * 4); }
;   for (int r = wave; r < M; r += nw) {
;     float* hp = hrow(p, r);
; #pragma unroll
;     for (int i = 0; i < 4; ++i) v[i] = vn[i];
;     if (r + nw < M) { const float* src = srcrow(r + nw);
; #pragma unroll
;       for (int i = 0; i < 4; ++i) vn[i] = *(const float4*)(src + i * 256 + lane * 4); }
;     if (nslab > 0 && r >= 32768) {
;       const float* sl = (const float*)(p.ws + OFF_SLAB) + (size_t)(r - 32768) * 1024 + lane * 4;
;       for (int sI = 0; sI < nslab; ++sI)
; #pragma unroll
;         for (int i = 0; i < 4; ++i) { const float4 a = *(const float4*)(sl + (size_t)sI * 131072 + i * 256); v[i].x += a.x; v[i].y += a.y; v[i].z += a.z; v[i].w += a.w; }
; #pragma unroll
;       for (int i = 0; i < 4; ++i) *(float4*)(hp + i * 256 + lane * 4) = v[i];
;     }
;     float ss = 0.f;
; #pragma unroll
;     for (int i = 0; i < 4; ++i) ss += v[i].x * v[i].x + v[i].y * v[i].y + v[i].z * v[i].z + v[i].w * v[i].w;
;     ss = wave_sum(ss);
;     const float rs = rsqrtf(ss * (1.0f / 1024.0f) + EPS);
; #pragma unroll
;     for (int i = 0; i < 4; ++i) {
;       const float4 g = *(const float4*)(gain + i * 256 + lane * 4);
;       uint2 w; w.x = pk_bf16(v[i].x * rs * g.x, v[i].y * rs * g.y); w.y = pk_bf16(v[i].z * rs * g.z, v[i].w * rs * g.w);
;       *(uint2*)(xn + (size_t)r * 1024 + i * 256 + lane * 4) = w;
;     }
;   }
.LBB0_2090:
	s_or_b64 exec, exec, s[0:1]
	v_readlane_b32 s0, v255, 4
	v_lshlrev_b64 v[0:1], 12, v[0:1]
	v_readlane_b32 s1, v255, 5
	v_lshl_add_u64 v[0:1], v[2:3], 0, v[0:1]
	v_lshlrev_b32_e32 v2, 2, v12
	s_mov_b32 s5, s1
	s_lshl_b32 s4, s56, 10
	v_writelane_b32 v255, s0, 4
	v_readlane_b32 s36, v253, 44
	v_and_b32_e32 v36, 0xfc, v2
	v_writelane_b32 v255, s1, 5
	s_lshl_b64 s[0:1], s[4:5], 2
	v_readlane_b32 s46, v253, 54
	v_lshlrev_b32_e32 v14, 2, v36
	v_mov_b32_e32 v15, v130
	v_readlane_b32 s47, v253, 55
	s_add_u32 s0, s46, s0
	v_lshl_add_u64 v[4:5], v[0:1], 0, v[14:15]
	s_addc_u32 s1, s47, s1
	global_load_dwordx4 v[0:3], v[4:5], off offset:3072
	global_load_dwordx4 v[8:11], v[4:5], off offset:2048
	global_load_dwordx4 v[28:31], v[4:5], off offset:1024
	global_load_dwordx4 v[32:35], v[4:5], off
	s_nop 0
	global_load_dwordx4 v[4:7], v14, s[0:1]
	v_cmp_lt_i32_e32 vcc, v185, v184
	v_lshl_add_u64 v[38:39], s[0:1], 0, v[14:15]
	global_load_dwordx4 v[112:115], v[38:39], off offset:1024
	global_load_dwordx4 v[116:119], v[38:39], off offset:2048
	global_load_dwordx4 v[120:123], v[38:39], off offset:3072
	s_waitcnt vmcnt(0)
	v_readlane_b32 s0, v254, 18
	v_cndmask_b32_e32 v13, v183, v185, vcc
	v_cmp_lt_i32_e32 vcc, v186, v184
	v_lshlrev_b32_e32 v37, 2, v13
	v_lshlrev_b32_e32 v14, 1, v36
	v_cndmask_b32_e32 v13, v183, v186, vcc
	v_cmp_lt_i32_e32 vcc, v187, v184
	v_lshlrev_b32_e32 v54, 2, v13
	v_readlane_b32 s1, v254, 19
	v_cndmask_b32_e32 v13, v183, v187, vcc
	v_cmp_lt_i32_e32 vcc, v191, v184
	v_lshlrev_b32_e32 v55, 2, v13
	v_lshl_add_u64 v[40:41], s[0:1], 0, v[14:15]
	v_cndmask_b32_e32 v13, v183, v191, vcc
	v_cmp_lt_i32_e32 vcc, v192, v184
	v_lshlrev_b32_e32 v56, 2, v13
	v_and_b32_e32 v12, 63, v12
	v_cndmask_b32_e32 v13, v183, v192, vcc
	v_cmp_lt_i32_e32 vcc, v190, v184
	v_lshlrev_b32_e32 v57, 2, v13
	v_readlane_b32 s0, v254, 25
	v_cndmask_b32_e32 v13, v183, v190, vcc
	s_and_b64 s[4:5], s[16:17], exec
	v_lshlrev_b32_e32 v58, 2, v13
	v_lshlrev_b32_e32 v12, 4, v12
	v_mov_b32_e32 v13, v130
	v_readlane_b32 s1, v254, 26
	s_cselect_b32 s18, 8, 4
	v_add_u32_e32 v44, 0xffff8000, v46
	v_lshl_add_u64 v[42:43], s[0:1], 0, v[12:13]
	s_mov_b64 s[4:5], 0
	v_readlane_b32 s37, v253, 45
	v_readlane_b32 s38, v253, 46
	v_readlane_b32 s39, v253, 47
	v_readlane_b32 s40, v253, 48
	v_readlane_b32 s41, v253, 49
	v_readlane_b32 s42, v253, 50
	v_readlane_b32 s43, v253, 51
	v_readlane_b32 s44, v253, 52
	v_readlane_b32 s45, v253, 53
	v_readlane_b32 s48, v253, 56
	v_readlane_b32 s49, v253, 57
	v_readlane_b32 s50, v253, 58
	v_readlane_b32 s51, v253, 59
	s_branch .LBB0_2092
.LBB0_2091:
	s_or_b64 exec, exec, s[0:1]
	v_mov_b32_e32 v48, v28
	v_mov_b32_e32 v49, v32
	v_pk_mul_f32 v[48:49], v[48:49], v[48:49]
	v_mov_b32_e32 v50, v29
	v_mov_b32_e32 v51, v33
	v_pk_fma_f32 v[48:49], v[50:51], v[50:51], v[48:49]
	v_mov_b32_e32 v50, v30
	v_mov_b32_e32 v51, v34
	v_pk_fma_f32 v[48:49], v[50:51], v[50:51], v[48:49]
	v_mov_b32_e32 v50, v31
	v_mov_b32_e32 v51, v35
	v_pk_fma_f32 v[48:49], v[50:51], v[50:51], v[48:49]
	v_mov_b32_e32 v50, v0
	v_mov_b32_e32 v51, v8
	v_pk_mul_f32 v[50:51], v[50:51], v[50:51]
	v_mov_b32_e32 v52, v1
	v_mov_b32_e32 v53, v9
	v_pk_fma_f32 v[50:51], v[52:53], v[52:53], v[50:51]
	v_mov_b32_e32 v52, v2
	v_mov_b32_e32 v53, v10
	v_pk_fma_f32 v[50:51], v[52:53], v[52:53], v[50:51]
	v_mov_b32_e32 v52, v3
	v_mov_b32_e32 v53, v11
	v_pk_fma_f32 v[50:51], v[52:53], v[52:53], v[50:51]
	v_add_f32_e32 v45, v48, v49
	v_add_f32_e32 v45, v51, v45
	v_add_f32_e32 v45, v50, v45
	v_add_u32_e32 v44, s80, v44
	s_nop 1
	v_add_f32_dpp v45, v45, v45 row_shr:1 row_mask:0xf bank_mask:0xf
	s_nop 1
	v_add_f32_dpp v45, v45, v45 row_shr:2 row_mask:0xf bank_mask:0xf
	s_nop 1
	v_add_f32_dpp v45, v45, v45 row_shr:4 row_mask:0xf bank_mask:0xf
	s_nop 1
	v_add_f32_dpp v45, v45, v45 row_shr:8 row_mask:0xf bank_mask:0xf
	s_nop 1
	v_add_f32_dpp v45, v45, v45 row_bcast:15 row_mask:0xa bank_mask:0xf
	s_nop 1
	v_add_f32_dpp v45, v45, v45 row_bcast:31 row_mask:0xc bank_mask:0xf
	s_nop 0
	v_readlane_b32 s98, v45, 63
	s_nop 1
	v_mov_b32_e32 v45, s98
	v_fmamk_f32 v45, v45, 0x3a800000, v132
	v_cmp_gt_f32_e32 vcc, s25, v45
	v_mul_f32_e32 v47, 0x4b800000, v45
	s_nop 0
	v_cndmask_b32_e32 v45, v45, v47, vcc
	v_rsq_f32_e32 v45, v45
	s_nop 0
	v_mul_f32_e32 v47, 0x45800000, v45
	v_cndmask_b32_e32 v45, v45, v47, vcc
	v_mul_f32_e32 v32, v32, v45
	v_mul_f32_e32 v33, v33, v45
	v_mul_f32_e32 v32, v4, v32
	v_mul_f32_e32 v33, v5, v33
	v_ashrrev_i32_e32 v47, 31, v46
	v_cvt_pk_bf16_f32 v32, v32, v33
	v_mul_f32_e32 v33, v34, v45
	v_lshlrev_b64 v[46:47], 11, v[46:47]
	v_mul_f32_e32 v33, v6, v33
	v_mul_f32_e32 v34, v35, v45
	v_lshl_add_u64 v[46:47], v[40:41], 0, v[46:47]
	v_mul_f32_e32 v34, v7, v34
	v_cvt_pk_bf16_f32 v33, v33, v34
	global_store_dwordx2 v[46:47], v[32:33], off
	v_mul_f32_e32 v28, v28, v45
	v_mul_f32_e32 v29, v29, v45
	v_mul_f32_e32 v8, v8, v45
	v_mul_f32_e32 v9, v9, v45
	v_mul_f32_e32 v0, v0, v45
	v_mul_f32_e32 v1, v1, v45
	v_mov_b64_e32 v[32:33], v[112:113]
	v_mov_b64_e32 v[34:35], v[114:115]
	v_mul_f32_e32 v28, v32, v28
	v_mul_f32_e32 v29, v33, v29
	v_cvt_pk_bf16_f32 v28, v28, v29
	v_mul_f32_e32 v29, v30, v45
	v_mul_f32_e32 v29, v34, v29
	v_mul_f32_e32 v30, v31, v45
	v_mul_f32_e32 v30, v35, v30
	v_cvt_pk_bf16_f32 v29, v29, v30
	global_store_dwordx2 v[46:47], v[28:29], off offset:512
	v_mov_b64_e32 v[28:29], v[116:117]
	v_mov_b64_e32 v[30:31], v[118:119]
	v_mul_f32_e32 v8, v28, v8
	v_mul_f32_e32 v9, v29, v9
	v_cvt_pk_bf16_f32 v8, v8, v9
	v_mul_f32_e32 v9, v10, v45
	v_mul_f32_e32 v9, v30, v9
	v_mul_f32_e32 v10, v11, v45
	v_mul_f32_e32 v10, v10, v31
	v_cvt_pk_bf16_f32 v9, v9, v10
	global_store_dwordx2 v[46:47], v[8:9], off offset:1024
	v_mov_b64_e32 v[8:9], v[120:121]
	v_mov_b64_e32 v[10:11], v[122:123]
	v_mul_f32_e32 v0, v0, v8
	v_mul_f32_e32 v1, v1, v9
	v_cvt_pk_bf16_f32 v0, v0, v1
	v_mul_f32_e32 v1, v2, v45
	v_mul_f32_e32 v1, v1, v10
	v_mul_f32_e32 v2, v3, v45
	v_mul_f32_e32 v2, v2, v11
	v_cvt_pk_bf16_f32 v1, v1, v2
	global_store_dwordx2 v[46:47], v[0:1], off offset:1536
	s_waitcnt vmcnt(4)
	v_mov_b64_e32 v[34:35], v[14:15]
	v_mov_b64_e32 v[32:33], v[12:13]
	v_mov_b64_e32 v[30:31], v[18:19]
	v_mov_b64_e32 v[28:29], v[16:17]
	v_mov_b32_e32 v46, v59
	v_mov_b64_e32 v[2:3], v[26:27]
	v_mov_b64_e32 v[0:1], v[24:25]
	v_mov_b64_e32 v[10:11], v[22:23]
	v_mov_b64_e32 v[8:9], v[20:21]
	s_andn2_b64 exec, exec, s[4:5]
	s_cbranch_execz .LBB0_2114
